# odin epilogue: V segment fast path too (direct dwordx2 transposed stores + f32 AV copy); the compiled odin epilogue is now unreachable for valid tiles
# baseline (speedup 1.0000x reference)
.LBB0_1518:
	s_lshr_b32 s12, s10, 10
	s_cmp_gt_u32 s12, 2
	s_cbranch_scc1 .Lodin4_old
	v_lshl_or_b32 v116, v183, 3, v191
	v_lshrrev_b32_e32 v117, 6, v116
	v_and_b32_e32 v118, 63, v116
	v_lshlrev_b32_e32 v113, 11, v117
	v_add_u32_e32 v113, 0x10000, v113
	v_readfirstlane_b32 s6, v117
	v_and_b32_e32 v116, 31, v118
	v_lshl_add_u32 v112, v116, 1, v113
	v_lshrrev_b32_e32 v117, 5, v118
	v_lshl_add_u32 v112, v117, 8, v112
	v_lshl_add_u32 v113, v118, 4, v113
	v_lshlrev_b32_e32 v115, 2, v116
	v_lshl_add_u32 v115, v117, 14, v115
	v_lshrrev_b32_e32 v117, 2, v118
	v_and_b32_e32 v114, 3, v118
	v_lshlrev_b32_e32 v114, 4, v114
	v_lshl_add_u32 v114, v117, 11, v114
	s_lshr_b32 s7, s6, 1
	s_lshl_b32 s7, s7, 6
	s_add_u32 s7, s7, s11
	s_and_b32 s6, s6, 1
	s_lshl_b32 s6, s6, 6
	s_and_b32 s8, s10, 0x3ff
	s_add_u32 s6, s6, s8
	s_cmp_eq_u32 s12, 2
	s_cbranch_scc1 .Lodin4_vseg
	s_cmp_ge_u32 s11, 0x2000
	s_cbranch_scc1 .Lodin4_rope

.Lodin4_vseg:
	s_cmp_ge_u32 s11, 0x2000
	s_cbranch_scc1 .Lodin4_vt
	s_lshl_b32 s8, s7, 12
	s_lshl_b32 s9, s6, 2
	s_add_u32 s8, s8, s9
	s_add_u32 s8, s8, 0x5000000
	s_add_u32 s98, s88, s8
	s_addc_u32 s99, s89, 0
	global_store_dword v115, v48, s[98:99]
	global_store_dword v115, v16, s[98:99] offset:128
	s_add_u32 s98, s98, 0x1000
	s_addc_u32 s99, s99, 0
	global_store_dword v115, v49, s[98:99]
	global_store_dword v115, v17, s[98:99] offset:128
	s_add_u32 s98, s98, 0x1000
	s_addc_u32 s99, s99, 0
	global_store_dword v115, v50, s[98:99]
	global_store_dword v115, v18, s[98:99] offset:128
	s_add_u32 s98, s98, 0x1000
	s_addc_u32 s99, s99, 0
	global_store_dword v115, v51, s[98:99]
	global_store_dword v115, v19, s[98:99] offset:128
	s_add_u32 s98, s98, 0x5000
	s_addc_u32 s99, s99, 0
	global_store_dword v115, v52, s[98:99]
	global_store_dword v115, v20, s[98:99] offset:128
	s_add_u32 s98, s98, 0x1000
	s_addc_u32 s99, s99, 0
	global_store_dword v115, v53, s[98:99]
	global_store_dword v115, v21, s[98:99] offset:128
	s_add_u32 s98, s98, 0x1000
	s_addc_u32 s99, s99, 0
	global_store_dword v115, v54, s[98:99]
	global_store_dword v115, v22, s[98:99] offset:128
	s_add_u32 s98, s98, 0x1000
	s_addc_u32 s99, s99, 0
	global_store_dword v115, v55, s[98:99]
	global_store_dword v115, v23, s[98:99] offset:128
	s_add_u32 s98, s98, 0x5000
	s_addc_u32 s99, s99, 0
	global_store_dword v115, v56, s[98:99]
	global_store_dword v115, v24, s[98:99] offset:128
	s_add_u32 s98, s98, 0x1000
	s_addc_u32 s99, s99, 0
	global_store_dword v115, v57, s[98:99]
	global_store_dword v115, v25, s[98:99] offset:128
	s_add_u32 s98, s98, 0x1000
	s_addc_u32 s99, s99, 0
	global_store_dword v115, v58, s[98:99]
	global_store_dword v115, v26, s[98:99] offset:128
	s_add_u32 s98, s98, 0x1000
	s_addc_u32 s99, s99, 0
	global_store_dword v115, v59, s[98:99]
	global_store_dword v115, v27, s[98:99] offset:128
	s_add_u32 s98, s98, 0x5000
	s_addc_u32 s99, s99, 0
	global_store_dword v115, v60, s[98:99]
	global_store_dword v115, v28, s[98:99] offset:128
	s_add_u32 s98, s98, 0x1000
	s_addc_u32 s99, s99, 0
	global_store_dword v115, v61, s[98:99]
	global_store_dword v115, v29, s[98:99] offset:128
	s_add_u32 s98, s98, 0x1000
	s_addc_u32 s99, s99, 0
	global_store_dword v115, v62, s[98:99]
	global_store_dword v115, v30, s[98:99] offset:128
	s_add_u32 s98, s98, 0x1000
	s_addc_u32 s99, s99, 0
	global_store_dword v115, v63, s[98:99]
	global_store_dword v115, v31, s[98:99] offset:128
	s_add_u32 s98, s98, 0x5000
	s_addc_u32 s99, s99, 0
	global_store_dword v115, v32, s[98:99]
	global_store_dword v115, v0, s[98:99] offset:128
	s_add_u32 s98, s98, 0x1000
	s_addc_u32 s99, s99, 0
	global_store_dword v115, v33, s[98:99]
	global_store_dword v115, v1, s[98:99] offset:128
	s_add_u32 s98, s98, 0x1000
	s_addc_u32 s99, s99, 0
	global_store_dword v115, v34, s[98:99]
	global_store_dword v115, v2, s[98:99] offset:128
	s_add_u32 s98, s98, 0x1000
	s_addc_u32 s99, s99, 0
	global_store_dword v115, v35, s[98:99]
	global_store_dword v115, v3, s[98:99] offset:128
	s_add_u32 s98, s98, 0x5000
	s_addc_u32 s99, s99, 0
	global_store_dword v115, v36, s[98:99]
	global_store_dword v115, v4, s[98:99] offset:128
	s_add_u32 s98, s98, 0x1000
	s_addc_u32 s99, s99, 0
	global_store_dword v115, v37, s[98:99]
	global_store_dword v115, v5, s[98:99] offset:128
	s_add_u32 s98, s98, 0x1000
	s_addc_u32 s99, s99, 0
	global_store_dword v115, v38, s[98:99]
	global_store_dword v115, v6, s[98:99] offset:128
	s_add_u32 s98, s98, 0x1000
	s_addc_u32 s99, s99, 0
	global_store_dword v115, v39, s[98:99]
	global_store_dword v115, v7, s[98:99] offset:128
	s_add_u32 s98, s98, 0x5000
	s_addc_u32 s99, s99, 0
	global_store_dword v115, v40, s[98:99]
	global_store_dword v115, v8, s[98:99] offset:128
	s_add_u32 s98, s98, 0x1000
	s_addc_u32 s99, s99, 0
	global_store_dword v115, v41, s[98:99]
	global_store_dword v115, v9, s[98:99] offset:128
	s_add_u32 s98, s98, 0x1000
	s_addc_u32 s99, s99, 0
	global_store_dword v115, v42, s[98:99]
	global_store_dword v115, v10, s[98:99] offset:128
	s_add_u32 s98, s98, 0x1000
	s_addc_u32 s99, s99, 0
	global_store_dword v115, v43, s[98:99]
	global_store_dword v115, v11, s[98:99] offset:128
	s_add_u32 s98, s98, 0x5000
	s_addc_u32 s99, s99, 0
	global_store_dword v115, v44, s[98:99]
	global_store_dword v115, v12, s[98:99] offset:128
	s_add_u32 s98, s98, 0x1000
	s_addc_u32 s99, s99, 0
	global_store_dword v115, v45, s[98:99]
	global_store_dword v115, v13, s[98:99] offset:128
	s_add_u32 s98, s98, 0x1000
	s_addc_u32 s99, s99, 0
	global_store_dword v115, v46, s[98:99]
	global_store_dword v115, v14, s[98:99] offset:128
	s_add_u32 s98, s98, 0x1000
	s_addc_u32 s99, s99, 0
	global_store_dword v115, v47, s[98:99]
	global_store_dword v115, v15, s[98:99] offset:128
.Lodin4_vt:
	v_and_b32_e32 v116, 31, v118
	v_mul_u32_u24_e32 v116, 0x6000, v116
	v_lshrrev_b32_e32 v117, 5, v118
	v_lshl_add_u32 v116, v117, 3, v116
	s_mul_i32 s8, s6, 0x6000
	s_lshl_b32 s9, s7, 1
	s_add_u32 s8, s8, s9
	s_add_u32 s8, s8, 0x6971900
	s_add_u32 s98, s90, s8
	s_addc_u32 s99, s91, 0
	s_add_u32 s100, s98, 0xc0000
	s_addc_u32 s101, s99, 0
	v_cvt_pk_bf16_f32 v64, v48, v49
	v_cvt_pk_bf16_f32 v65, v50, v51
	global_store_dwordx2 v116, v[64:65], s[98:99]
	v_cvt_pk_bf16_f32 v66, v52, v53
	v_cvt_pk_bf16_f32 v67, v54, v55
	global_store_dwordx2 v116, v[66:67], s[98:99] offset:16
	v_cvt_pk_bf16_f32 v68, v56, v57
	v_cvt_pk_bf16_f32 v69, v58, v59
	global_store_dwordx2 v116, v[68:69], s[98:99] offset:32
	v_cvt_pk_bf16_f32 v70, v60, v61
	v_cvt_pk_bf16_f32 v71, v62, v63
	global_store_dwordx2 v116, v[70:71], s[98:99] offset:48
	v_cvt_pk_bf16_f32 v72, v32, v33
	v_cvt_pk_bf16_f32 v73, v34, v35
	global_store_dwordx2 v116, v[72:73], s[98:99] offset:64
	v_cvt_pk_bf16_f32 v74, v36, v37
	v_cvt_pk_bf16_f32 v75, v38, v39
	global_store_dwordx2 v116, v[74:75], s[98:99] offset:80
	v_cvt_pk_bf16_f32 v76, v40, v41
	v_cvt_pk_bf16_f32 v77, v42, v43
	global_store_dwordx2 v116, v[76:77], s[98:99] offset:96
	v_cvt_pk_bf16_f32 v78, v44, v45
	v_cvt_pk_bf16_f32 v79, v46, v47
	global_store_dwordx2 v116, v[78:79], s[98:99] offset:112
	v_cvt_pk_bf16_f32 v80, v16, v17
	v_cvt_pk_bf16_f32 v81, v18, v19
	global_store_dwordx2 v116, v[80:81], s[100:101]
	v_cvt_pk_bf16_f32 v82, v20, v21
	v_cvt_pk_bf16_f32 v83, v22, v23
	global_store_dwordx2 v116, v[82:83], s[100:101] offset:16
	v_cvt_pk_bf16_f32 v84, v24, v25
	v_cvt_pk_bf16_f32 v85, v26, v27
	global_store_dwordx2 v116, v[84:85], s[100:101] offset:32
	v_cvt_pk_bf16_f32 v86, v28, v29
	v_cvt_pk_bf16_f32 v87, v30, v31
	global_store_dwordx2 v116, v[86:87], s[100:101] offset:48
	v_cvt_pk_bf16_f32 v88, v0, v1
	v_cvt_pk_bf16_f32 v89, v2, v3
	global_store_dwordx2 v116, v[88:89], s[100:101] offset:64
	v_cvt_pk_bf16_f32 v90, v4, v5
	v_cvt_pk_bf16_f32 v91, v6, v7
	global_store_dwordx2 v116, v[90:91], s[100:101] offset:80
	v_cvt_pk_bf16_f32 v92, v8, v9
	v_cvt_pk_bf16_f32 v93, v10, v11
	global_store_dwordx2 v116, v[92:93], s[100:101] offset:96
	v_cvt_pk_bf16_f32 v94, v12, v13
	v_cvt_pk_bf16_f32 v95, v14, v15
	global_store_dwordx2 v116, v[94:95], s[100:101] offset:112
	s_branch .Lodin4_next
